# attention subln epilogue: next group's weight load issued before the widened store and waited with vmcnt(1), on top of the ss-prefetch version
# speedup vs baseline: 1.0021x; 1.0021x over previous
; __device__ __forceinline__ float bf_lo(unsigned u) { return __uint_as_float(u << 16); }
; __device__ __forceinline__ float bf_hi(unsigned u) { return __uint_as_float(u & 0xffff0000u); }
; __device__ void attn_tile(CP& p, const Grp& G, int s, int hd, int qb, char* lds, float lam) {
;     ...
;       const float i2 = lam / lt;
;       float ssq = 0.f;
; #pragma unroll
;       for (int mb = 0; mb < 4; ++mb)
; #pragma unroll
;         for (int i = 0; i < 4; ++i) {
;           u32x2 w = {0, 0};
;           if (q < L) w = *(const u32x2*)(odst + mb * 32 + 8 * i + 4 * h);
;           const float o0 = bf_lo(w.x) - O[mb][4 * i] * i2, o1v = bf_hi(w.x) - O[mb][4 * i + 1] * i2, o2 = bf_lo(w.y) - O[mb][4 * i + 2] * i2, o3 = bf_hi(w.y) - O[mb][4 * i + 3] * i2;
;           O[mb][4 * i] = o0; O[mb][4 * i + 1] = o1v; O[mb][4 * i + 2] = o2; O[mb][4 * i + 3] = o3;
;           ssq += o0 * o0 + o1v * o1v + o2 * o2 + o3 * o3;
;         }
;       ssq += __shfl_xor(ssq, 32);
.LBB0_441:
	s_or_b64 exec, exec, s[0:1]
	v_div_scale_f32 v64, s[0:1], v128, v128, v163
	v_rcp_f32_e32 v65, v64
	v_div_scale_f32 v68, vcc, v163, v128, v163
	v_fma_f32 v69, -v64, v65, 1.0
	v_fmac_f32_e32 v65, v69, v65
	v_mul_f32_e32 v69, v68, v65
	v_fma_f32 v72, -v64, v69, v68
	v_fmac_f32_e32 v69, v72, v65
	v_fma_f32 v64, -v64, v69, v68
	v_div_fmas_f32 v64, v64, v65, v69
	v_div_fixup_f32 v130, v64, v128, v163
	s_waitcnt vmcnt(0)
	v_lshlrev_b32_e32 v64, 16, v66
	v_and_b32_e32 v65, 0xffff0000, v66
	v_lshlrev_b32_e32 v66, 16, v67
	v_and_b32_e32 v67, 0xffff0000, v67
	v_pk_fma_f32 v[68:69], v[50:51], v[130:131], v[66:67] op_sel_hi:[1,0,1] neg_lo:[1,0,0] neg_hi:[1,0,0]
	v_lshlrev_b32_e32 v66, 16, v70
	v_and_b32_e32 v67, 0xffff0000, v70
	v_lshlrev_b32_e32 v70, 16, v71
	v_and_b32_e32 v71, 0xffff0000, v71
	v_pk_fma_f32 v[64:65], v[48:49], v[130:131], v[64:65] op_sel_hi:[1,0,1] neg_lo:[1,0,0] neg_hi:[1,0,0]
	v_pk_fma_f32 v[66:67], v[52:53], v[130:131], v[66:67] op_sel_hi:[1,0,1] neg_lo:[1,0,0] neg_hi:[1,0,0]
	v_pk_fma_f32 v[72:73], v[54:55], v[130:131], v[70:71] op_sel_hi:[1,0,1] neg_lo:[1,0,0] neg_hi:[1,0,0]
	v_lshlrev_b32_e32 v70, 16, v74
	v_and_b32_e32 v71, 0xffff0000, v74
	v_pk_mul_f32 v[132:133], v[64:65], v[64:65]
	v_pk_mul_f32 v[136:137], v[66:67], v[66:67]
	v_pk_fma_f32 v[70:71], v[56:57], v[130:131], v[70:71] op_sel_hi:[1,0,1] neg_lo:[1,0,0] neg_hi:[1,0,0]
	v_lshlrev_b32_e32 v74, 16, v75
	v_and_b32_e32 v75, 0xffff0000, v75
	v_pk_mul_f32 v[134:135], v[68:69], v[68:69]
	v_pk_mul_f32 v[138:139], v[72:73], v[72:73]
	v_pk_fma_f32 v[78:79], v[58:59], v[130:131], v[74:75] op_sel_hi:[1,0,1] neg_lo:[1,0,0] neg_hi:[1,0,0]
	v_pk_mul_f32 v[140:141], v[70:71], v[70:71]
	v_add_f32_e32 v136, v136, v137
	v_add_f32_e32 v132, v132, v133
	v_pk_mul_f32 v[142:143], v[78:79], v[78:79]
	v_lshlrev_b32_e32 v74, 16, v76
	v_and_b32_e32 v75, 0xffff0000, v76
	v_add_f32_e32 v136, v138, v136
	v_add_f32_e32 v132, v134, v132
	v_add_f32_e32 v133, v140, v141
	v_pk_fma_f32 v[74:75], v[60:61], v[130:131], v[74:75] op_sel_hi:[1,0,1] neg_lo:[1,0,0] neg_hi:[1,0,0]
	v_lshlrev_b32_e32 v76, 16, v77
	v_and_b32_e32 v77, 0xffff0000, v77
	v_add_f32_e32 v136, v139, v136
	v_add_f32_e32 v132, v135, v132
	v_add_f32_e32 v133, v142, v133
	v_pk_fma_f32 v[82:83], v[62:63], v[130:131], v[76:77] op_sel_hi:[1,0,1] neg_lo:[1,0,0] neg_hi:[1,0,0]
	v_pk_mul_f32 v[144:145], v[74:75], v[74:75]
	v_add_f32_e32 v132, v132, v136
	v_add_f32_e32 v133, v143, v133
	v_pk_mul_f32 v[146:147], v[82:83], v[82:83]
	v_lshlrev_b32_e32 v76, 16, v80
	v_and_b32_e32 v77, 0xffff0000, v80
	v_add_f32_e32 v132, v132, v133
	v_add_f32_e32 v133, v144, v145
	v_pk_fma_f32 v[76:77], v[32:33], v[130:131], v[76:77] op_sel_hi:[1,0,1] neg_lo:[1,0,0] neg_hi:[1,0,0]
	v_lshlrev_b32_e32 v80, 16, v81
	v_and_b32_e32 v81, 0xffff0000, v81
	v_add_f32_e32 v133, v146, v133
	v_pk_fma_f32 v[84:85], v[34:35], v[130:131], v[80:81] op_sel_hi:[1,0,1] neg_lo:[1,0,0] neg_hi:[1,0,0]
	v_pk_mul_f32 v[148:149], v[76:77], v[76:77]
	v_add_f32_e32 v133, v147, v133
	v_pk_mul_f32 v[150:151], v[84:85], v[84:85]
	v_lshlrev_b32_e32 v80, 16, v86
	v_and_b32_e32 v81, 0xffff0000, v86
	v_add_f32_e32 v132, v132, v133
	v_add_f32_e32 v133, v148, v149
	v_pk_fma_f32 v[80:81], v[36:37], v[130:131], v[80:81] op_sel_hi:[1,0,1] neg_lo:[1,0,0] neg_hi:[1,0,0]
	v_lshlrev_b32_e32 v86, 16, v87
	v_and_b32_e32 v87, 0xffff0000, v87
	v_add_f32_e32 v133, v150, v133
	v_pk_fma_f32 v[88:89], v[38:39], v[130:131], v[86:87] op_sel_hi:[1,0,1] neg_lo:[1,0,0] neg_hi:[1,0,0]
	v_pk_mul_f32 v[152:153], v[80:81], v[80:81]
	v_add_f32_e32 v133, v151, v133
	v_pk_mul_f32 v[154:155], v[88:89], v[88:89]
	v_lshlrev_b32_e32 v86, 16, v90
	v_and_b32_e32 v87, 0xffff0000, v90
	v_add_f32_e32 v132, v132, v133
	v_add_f32_e32 v133, v152, v153
	v_pk_fma_f32 v[86:87], v[40:41], v[130:131], v[86:87] op_sel_hi:[1,0,1] neg_lo:[1,0,0] neg_hi:[1,0,0]
	v_lshlrev_b32_e32 v90, 16, v91
	v_and_b32_e32 v91, 0xffff0000, v91
	v_add_f32_e32 v133, v154, v133
	v_pk_fma_f32 v[94:95], v[42:43], v[130:131], v[90:91] op_sel_hi:[1,0,1] neg_lo:[1,0,0] neg_hi:[1,0,0]
	v_pk_mul_f32 v[156:157], v[86:87], v[86:87]
	v_add_f32_e32 v133, v155, v133
	v_pk_mul_f32 v[158:159], v[94:95], v[94:95]
	v_lshlrev_b32_e32 v90, 16, v92
	v_and_b32_e32 v91, 0xffff0000, v92
	v_add_f32_e32 v132, v132, v133
	v_add_f32_e32 v133, v156, v157
	v_pk_fma_f32 v[90:91], v[44:45], v[130:131], v[90:91] op_sel_hi:[1,0,1] neg_lo:[1,0,0] neg_hi:[1,0,0]
	v_lshlrev_b32_e32 v92, 16, v93
	v_and_b32_e32 v93, 0xffff0000, v93
	v_add_f32_e32 v133, v158, v133
	v_pk_fma_f32 v[98:99], v[46:47], v[130:131], v[92:93] op_sel_hi:[1,0,1] neg_lo:[1,0,0] neg_hi:[1,0,0]
	v_pk_mul_f32 v[190:191], v[90:91], v[90:91]
	v_add_f32_e32 v133, v159, v133
	v_pk_mul_f32 v[192:193], v[98:99], v[98:99]
	v_lshlrev_b32_e32 v92, 16, v96
	v_and_b32_e32 v93, 0xffff0000, v96
	v_add_f32_e32 v132, v132, v133
	v_add_f32_e32 v133, v190, v191
	v_pk_fma_f32 v[92:93], v[16:17], v[130:131], v[92:93] op_sel_hi:[1,0,1] neg_lo:[1,0,0] neg_hi:[1,0,0]
	v_lshlrev_b32_e32 v96, 16, v97
	v_and_b32_e32 v97, 0xffff0000, v97
	v_add_f32_e32 v133, v192, v133
	v_pk_fma_f32 v[100:101], v[18:19], v[130:131], v[96:97] op_sel_hi:[1,0,1] neg_lo:[1,0,0] neg_hi:[1,0,0]
	v_pk_mul_f32 v[194:195], v[92:93], v[92:93]
	v_add_f32_e32 v133, v193, v133
	v_pk_mul_f32 v[196:197], v[100:101], v[100:101]
	v_lshlrev_b32_e32 v96, 16, v102
	v_and_b32_e32 v97, 0xffff0000, v102
	v_add_f32_e32 v132, v132, v133
	v_add_f32_e32 v133, v194, v195
	v_pk_fma_f32 v[96:97], v[20:21], v[130:131], v[96:97] op_sel_hi:[1,0,1] neg_lo:[1,0,0] neg_hi:[1,0,0]
	v_lshlrev_b32_e32 v102, 16, v103
	v_and_b32_e32 v103, 0xffff0000, v103
	v_add_f32_e32 v133, v196, v133
; __device__ void attn_tile(CP& p, const Grp& G, int s, int hd, int qb, char* lds, float lam) {
;     ...
;       ssq += __shfl_xor(ssq, 32);
;       const float rn = rsqrtf(ssq * (1.f / 128.f) + EPSN) * 0.8f;
;       if (q < L) {
; #pragma unroll
;         for (int mb = 0; mb < 4; ++mb)
; #pragma unroll
;           for (int i = 0; i < 4; ++i) {
;             const int dv = mb * 32 + 8 * i + 4 * h;
;             const f32x4 g = *(const f32x4*)(p.subln + dv);
;             *(u32x2*)(odst + dv) = (u32x2){pk_bf16(O[mb][4 * i] * rn * g.x, O[mb][4 * i + 1] * rn * g.y),
;                                            pk_bf16(O[mb][4 * i + 2] * rn * g.z, O[mb][4 * i + 3] * rn * g.w)};
;           }
	v_pk_fma_f32 v[104:105], v[22:23], v[130:131], v[102:103] op_sel_hi:[1,0,1] neg_lo:[1,0,0] neg_hi:[1,0,0]
	v_pk_mul_f32 v[198:199], v[96:97], v[96:97]
	v_add_f32_e32 v133, v197, v133
	v_pk_mul_f32 v[200:201], v[104:105], v[104:105]
	v_lshlrev_b32_e32 v102, 16, v106
	v_and_b32_e32 v103, 0xffff0000, v106
	v_add_f32_e32 v132, v132, v133
	v_add_f32_e32 v133, v198, v199
	v_pk_fma_f32 v[102:103], v[24:25], v[130:131], v[102:103] op_sel_hi:[1,0,1] neg_lo:[1,0,0] neg_hi:[1,0,0]
	v_lshlrev_b32_e32 v106, 16, v107
	v_and_b32_e32 v107, 0xffff0000, v107
	v_add_f32_e32 v133, v200, v133
	v_pk_fma_f32 v[110:111], v[26:27], v[130:131], v[106:107] op_sel_hi:[1,0,1] neg_lo:[1,0,0] neg_hi:[1,0,0]
	v_pk_mul_f32 v[202:203], v[102:103], v[102:103]
	v_add_f32_e32 v133, v201, v133
	v_pk_mul_f32 v[232:233], v[110:111], v[110:111]
	v_lshlrev_b32_e32 v106, 16, v108
	v_and_b32_e32 v107, 0xffff0000, v108
	v_add_f32_e32 v132, v132, v133
	v_add_f32_e32 v133, v202, v203
	v_pk_fma_f32 v[106:107], v[28:29], v[130:131], v[106:107] op_sel_hi:[1,0,1] neg_lo:[1,0,0] neg_hi:[1,0,0]
	v_lshlrev_b32_e32 v108, 16, v109
	v_and_b32_e32 v109, 0xffff0000, v109
	v_add_f32_e32 v133, v232, v133
	v_pk_fma_f32 v[114:115], v[30:31], v[130:131], v[108:109] op_sel_hi:[1,0,1] neg_lo:[1,0,0] neg_hi:[1,0,0]
	v_pk_mul_f32 v[234:235], v[106:107], v[106:107]
	v_add_f32_e32 v133, v233, v133
	v_pk_mul_f32 v[236:237], v[114:115], v[114:115]
	v_lshlrev_b32_e32 v108, 16, v112
	v_and_b32_e32 v109, 0xffff0000, v112
	v_add_f32_e32 v132, v132, v133
	v_add_f32_e32 v133, v234, v235
	v_pk_fma_f32 v[108:109], v[0:1], v[130:131], v[108:109] op_sel_hi:[1,0,1] neg_lo:[1,0,0] neg_hi:[1,0,0]
	v_lshlrev_b32_e32 v112, 16, v113
	v_and_b32_e32 v113, 0xffff0000, v113
	v_add_f32_e32 v133, v236, v133
	v_pk_fma_f32 v[116:117], v[2:3], v[130:131], v[112:113] op_sel_hi:[1,0,1] neg_lo:[1,0,0] neg_hi:[1,0,0]
	v_pk_mul_f32 v[238:239], v[108:109], v[108:109]
	v_add_f32_e32 v133, v237, v133
	v_pk_mul_f32 v[240:241], v[116:117], v[116:117]
	v_lshlrev_b32_e32 v112, 16, v118
	v_and_b32_e32 v113, 0xffff0000, v118
	v_add_f32_e32 v132, v132, v133
	v_add_f32_e32 v133, v238, v239
	v_pk_fma_f32 v[112:113], v[4:5], v[130:131], v[112:113] op_sel_hi:[1,0,1] neg_lo:[1,0,0] neg_hi:[1,0,0]
	v_lshlrev_b32_e32 v118, 16, v119
	v_and_b32_e32 v119, 0xffff0000, v119
	v_add_f32_e32 v133, v240, v133
	v_pk_fma_f32 v[120:121], v[6:7], v[130:131], v[118:119] op_sel_hi:[1,0,1] neg_lo:[1,0,0] neg_hi:[1,0,0]
	v_pk_mul_f32 v[242:243], v[112:113], v[112:113]
	v_add_f32_e32 v133, v241, v133
	v_pk_mul_f32 v[244:245], v[120:121], v[120:121]
	v_lshlrev_b32_e32 v118, 16, v122
	v_and_b32_e32 v119, 0xffff0000, v122
	v_lshlrev_b32_e32 v122, 16, v123
	v_and_b32_e32 v123, 0xffff0000, v123
	v_add_f32_e32 v132, v132, v133
	v_add_f32_e32 v133, v242, v243
	v_pk_fma_f32 v[118:119], v[8:9], v[130:131], v[118:119] op_sel_hi:[1,0,1] neg_lo:[1,0,0] neg_hi:[1,0,0]
	v_pk_fma_f32 v[124:125], v[10:11], v[130:131], v[122:123] op_sel_hi:[1,0,1] neg_lo:[1,0,0] neg_hi:[1,0,0]
	v_lshlrev_b32_e32 v122, 16, v126
	v_and_b32_e32 v123, 0xffff0000, v126
	v_add_f32_e32 v133, v244, v133
	v_pk_mul_f32 v[246:247], v[118:119], v[118:119]
	v_pk_fma_f32 v[122:123], v[12:13], v[130:131], v[122:123] op_sel_hi:[1,0,1] neg_lo:[1,0,0] neg_hi:[1,0,0]
	v_lshlrev_b32_e32 v126, 16, v127
	v_and_b32_e32 v127, 0xffff0000, v127
	v_add_f32_e32 v133, v245, v133
	v_pk_mul_f32 v[248:249], v[124:125], v[124:125]
	v_pk_fma_f32 v[126:127], v[14:15], v[130:131], v[126:127] op_sel_hi:[1,0,1] neg_lo:[1,0,0] neg_hi:[1,0,0]
	v_pk_mul_f32 v[130:131], v[122:123], v[122:123]
	v_add_f32_e32 v132, v132, v133
	v_add_f32_e32 v133, v246, v247
	v_pk_mul_f32 v[250:251], v[126:127], v[126:127]
	v_add_f32_e32 v133, v248, v133
	v_add_f32_e32 v130, v130, v131
	v_add_f32_e32 v133, v249, v133
	v_add_f32_e32 v130, v250, v130
	v_add_f32_e32 v132, v132, v133
	v_add_f32_e32 v130, v251, v130
	v_add_f32_e32 v130, v132, v130
	ds_bpermute_b32 v129, v129, v130
	s_and_saveexec_b64 s[34:35], s[38:39]
	s_cbranch_execz .LBB0_443
	global_load_dwordx4 v[132:135], v[176:177], off
	s_waitcnt lgkmcnt(0)
	v_add_f32_e32 v129, v130, v129
	v_fmamk_f32 v129, v129, 0x3c000000, v205
	v_mul_f32_e32 v130, 0x4b800000, v129
	v_cmp_gt_f32_e32 vcc, s21, v129
	s_nop 1
	v_cndmask_b32_e32 v129, v129, v130, vcc
	v_rsq_f32_e32 v129, v129
	s_nop 0
	v_mul_f32_e32 v130, 0x45800000, v129
	v_cndmask_b32_e32 v129, v129, v130, vcc
	v_mul_f32_e32 v136, 0x3f4ccccd, v129
	v_pk_mul_f32 v[64:65], v[64:65], v[136:137] op_sel_hi:[1,0]
	v_pk_mul_f32 v[68:69], v[68:69], v[136:137] op_sel_hi:[1,0]
	s_waitcnt vmcnt(0)
	v_pk_mul_f32 v[64:65], v[64:65], v[132:133]
	v_pk_mul_f32 v[68:69], v[68:69], v[134:135]
	v_cvt_pk_bf16_f32 v64, v64, v65
	v_cvt_pk_bf16_f32 v65, v68, v69
	v_mbcnt_lo_u32_b32 v250, -1, 0
	v_mbcnt_hi_u32_b32 v250, -1, v250
	v_lshrrev_b32_e32 v250, 2, v250
	v_and_b32_e32 v250, 8, v250
	v_mov_b32_e32 v251, 0
	v_lshl_add_u64 v[250:251], v[174:175], 0, v[250:251]
	v_mov_b32_e32 v238, v64
	v_mov_b32_e32 v239, v65
	global_load_dwordx4 v[130:133], v[176:177], off offset:32
	v_pk_mul_f32 v[64:65], v[66:67], v[136:137] op_sel_hi:[1,0]
	v_pk_mul_f32 v[66:67], v[72:73], v[136:137] op_sel_hi:[1,0]
	v_pk_mul_f32 v[68:69], v[70:71], v[136:137] op_sel_hi:[1,0]
	v_pk_mul_f32 v[70:71], v[78:79], v[136:137] op_sel_hi:[1,0]
	s_waitcnt vmcnt(0)
	v_pk_mul_f32 v[64:65], v[64:65], v[130:131]
	v_pk_mul_f32 v[66:67], v[66:67], v[132:133]
	v_cvt_pk_bf16_f32 v64, v64, v65
	v_cvt_pk_bf16_f32 v65, v66, v67
	v_mov_b32_e32 v240, v64
	v_mov_b32_e32 v241, v65
	global_load_dwordx4 v[64:67], v[176:177], off offset:64
	s_nop 1
	v_permlane32_swap_b32_e32 v238, v240
	v_permlane32_swap_b32_e32 v239, v241
	global_store_dwordx4 v[250:251], v[238:241], off
	s_waitcnt vmcnt(1)
; __device__ void attn_tile(CP& p, const Grp& G, int s, int hd, int qb, char* lds, float lam) {
;     ...
;       if (q < L) {
; #pragma unroll
;         for (int mb = 0; mb < 4; ++mb)
; #pragma unroll
;           for (int i = 0; i < 4; ++i) {
;             const int dv = mb * 32 + 8 * i + 4 * h;
;             const f32x4 g = *(const f32x4*)(p.subln + dv);
;             *(u32x2*)(odst + dv) = (u32x2){pk_bf16(O[mb][4 * i] * rn * g.x, O[mb][4 * i + 1] * rn * g.y),
;                                            pk_bf16(O[mb][4 * i + 2] * rn * g.z, O[mb][4 * i + 3] * rn * g.w)};
;           }
	v_pk_mul_f32 v[64:65], v[68:69], v[64:65]
	v_pk_mul_f32 v[66:67], v[70:71], v[66:67]
	v_cvt_pk_bf16_f32 v64, v64, v65
	v_cvt_pk_bf16_f32 v65, v66, v67
	v_mov_b32_e32 v242, v64
	v_mov_b32_e32 v243, v65
	global_load_dwordx4 v[64:67], v[176:177], off offset:96
	v_pk_mul_f32 v[68:69], v[74:75], v[136:137] op_sel_hi:[1,0]
	v_pk_mul_f32 v[70:71], v[82:83], v[136:137] op_sel_hi:[1,0]
	s_waitcnt vmcnt(0)
	v_pk_mul_f32 v[64:65], v[68:69], v[64:65]
	v_pk_mul_f32 v[66:67], v[70:71], v[66:67]
	v_cvt_pk_bf16_f32 v64, v64, v65
	v_cvt_pk_bf16_f32 v65, v66, v67
	v_mov_b32_e32 v244, v64
	v_mov_b32_e32 v245, v65
	global_load_dwordx4 v[64:67], v[176:177], off offset:128
	s_nop 1
	v_permlane32_swap_b32_e32 v242, v244
	v_permlane32_swap_b32_e32 v243, v245
	global_store_dwordx4 v[250:251], v[242:245], off offset:32
	v_pk_mul_f32 v[68:69], v[76:77], v[136:137] op_sel_hi:[1,0]
	v_pk_mul_f32 v[70:71], v[84:85], v[136:137] op_sel_hi:[1,0]
	s_waitcnt vmcnt(1)
	v_pk_mul_f32 v[64:65], v[68:69], v[64:65]
	v_pk_mul_f32 v[66:67], v[70:71], v[66:67]
	v_cvt_pk_bf16_f32 v64, v64, v65
	v_cvt_pk_bf16_f32 v65, v66, v67
	v_mov_b32_e32 v246, v64
	v_mov_b32_e32 v247, v65
	global_load_dwordx4 v[64:67], v[176:177], off offset:160
	v_pk_mul_f32 v[68:69], v[80:81], v[136:137] op_sel_hi:[1,0]
	v_pk_mul_f32 v[70:71], v[88:89], v[136:137] op_sel_hi:[1,0]
	s_waitcnt vmcnt(0)
	v_pk_mul_f32 v[64:65], v[68:69], v[64:65]
	v_pk_mul_f32 v[66:67], v[70:71], v[66:67]
	v_cvt_pk_bf16_f32 v64, v64, v65
	v_cvt_pk_bf16_f32 v65, v66, v67
	v_mov_b32_e32 v248, v64
	v_mov_b32_e32 v249, v65
	global_load_dwordx4 v[64:67], v[176:177], off offset:192
	s_nop 1
	v_permlane32_swap_b32_e32 v246, v248
	v_permlane32_swap_b32_e32 v247, v249
	global_store_dwordx4 v[250:251], v[246:249], off offset:64
	v_pk_mul_f32 v[68:69], v[86:87], v[136:137] op_sel_hi:[1,0]
	v_pk_mul_f32 v[70:71], v[94:95], v[136:137] op_sel_hi:[1,0]
	s_waitcnt vmcnt(1)
	v_pk_mul_f32 v[64:65], v[68:69], v[64:65]
	v_pk_mul_f32 v[66:67], v[70:71], v[66:67]
	v_cvt_pk_bf16_f32 v64, v64, v65
	v_cvt_pk_bf16_f32 v65, v66, v67
	v_mov_b32_e32 v238, v64
	v_mov_b32_e32 v239, v65
	global_load_dwordx4 v[64:67], v[176:177], off offset:224
	v_pk_mul_f32 v[68:69], v[90:91], v[136:137] op_sel_hi:[1,0]
	v_pk_mul_f32 v[70:71], v[98:99], v[136:137] op_sel_hi:[1,0]
	s_waitcnt vmcnt(0)
	v_pk_mul_f32 v[64:65], v[68:69], v[64:65]
	v_pk_mul_f32 v[66:67], v[70:71], v[66:67]
	v_cvt_pk_bf16_f32 v64, v64, v65
	v_cvt_pk_bf16_f32 v65, v66, v67
	v_mov_b32_e32 v240, v64
	v_mov_b32_e32 v241, v65
	global_load_dwordx4 v[64:67], v[176:177], off offset:256
	s_nop 1
	v_permlane32_swap_b32_e32 v238, v240
	v_permlane32_swap_b32_e32 v239, v241
	global_store_dwordx4 v[250:251], v[238:241], off offset:96
	v_pk_mul_f32 v[68:69], v[92:93], v[136:137] op_sel_hi:[1,0]
	v_pk_mul_f32 v[70:71], v[100:101], v[136:137] op_sel_hi:[1,0]
	s_waitcnt vmcnt(1)
	v_pk_mul_f32 v[64:65], v[68:69], v[64:65]
	v_pk_mul_f32 v[66:67], v[70:71], v[66:67]
	v_cvt_pk_bf16_f32 v64, v64, v65
	v_cvt_pk_bf16_f32 v65, v66, v67
	v_mov_b32_e32 v242, v64
	v_mov_b32_e32 v243, v65
	global_load_dwordx4 v[64:67], v[176:177], off offset:288
	v_pk_mul_f32 v[68:69], v[96:97], v[136:137] op_sel_hi:[1,0]
	v_pk_mul_f32 v[70:71], v[104:105], v[136:137] op_sel_hi:[1,0]
	s_waitcnt vmcnt(0)
	v_pk_mul_f32 v[64:65], v[68:69], v[64:65]
	v_pk_mul_f32 v[66:67], v[70:71], v[66:67]
	v_cvt_pk_bf16_f32 v64, v64, v65
	v_cvt_pk_bf16_f32 v65, v66, v67
	v_mov_b32_e32 v244, v64
	v_mov_b32_e32 v245, v65
	global_load_dwordx4 v[64:67], v[176:177], off offset:320
	s_nop 1
	v_permlane32_swap_b32_e32 v242, v244
	v_permlane32_swap_b32_e32 v243, v245
	global_store_dwordx4 v[250:251], v[242:245], off offset:128
	v_pk_mul_f32 v[68:69], v[102:103], v[136:137] op_sel_hi:[1,0]
	v_pk_mul_f32 v[70:71], v[110:111], v[136:137] op_sel_hi:[1,0]
	s_waitcnt vmcnt(1)
	v_pk_mul_f32 v[64:65], v[68:69], v[64:65]
	v_pk_mul_f32 v[66:67], v[70:71], v[66:67]
	v_cvt_pk_bf16_f32 v64, v64, v65
	v_cvt_pk_bf16_f32 v65, v66, v67
	v_mov_b32_e32 v246, v64
	v_mov_b32_e32 v247, v65
	global_load_dwordx4 v[64:67], v[176:177], off offset:352
	v_pk_mul_f32 v[68:69], v[106:107], v[136:137] op_sel_hi:[1,0]
	v_pk_mul_f32 v[70:71], v[114:115], v[136:137] op_sel_hi:[1,0]
	s_waitcnt vmcnt(0)
	v_pk_mul_f32 v[64:65], v[68:69], v[64:65]
	v_pk_mul_f32 v[66:67], v[70:71], v[66:67]
	v_cvt_pk_bf16_f32 v64, v64, v65
	v_cvt_pk_bf16_f32 v65, v66, v67
	v_mov_b32_e32 v248, v64
	v_mov_b32_e32 v249, v65
	global_load_dwordx4 v[64:67], v[176:177], off offset:384
	s_nop 1
	v_permlane32_swap_b32_e32 v246, v248
	v_permlane32_swap_b32_e32 v247, v249
	global_store_dwordx4 v[250:251], v[246:249], off offset:160
	v_pk_mul_f32 v[68:69], v[108:109], v[136:137] op_sel_hi:[1,0]
	v_pk_mul_f32 v[70:71], v[116:117], v[136:137] op_sel_hi:[1,0]
	s_waitcnt vmcnt(1)
	v_pk_mul_f32 v[64:65], v[68:69], v[64:65]
	v_pk_mul_f32 v[66:67], v[70:71], v[66:67]
	v_cvt_pk_bf16_f32 v64, v64, v65
	v_cvt_pk_bf16_f32 v65, v66, v67
	v_mov_b32_e32 v238, v64
	v_mov_b32_e32 v239, v65
	global_load_dwordx4 v[64:67], v[176:177], off offset:416
	v_pk_mul_f32 v[68:69], v[112:113], v[136:137] op_sel_hi:[1,0]
	v_pk_mul_f32 v[70:71], v[120:121], v[136:137] op_sel_hi:[1,0]
	s_waitcnt vmcnt(0)
	v_pk_mul_f32 v[64:65], v[68:69], v[64:65]
	v_pk_mul_f32 v[66:67], v[70:71], v[66:67]
	v_cvt_pk_bf16_f32 v64, v64, v65
	v_cvt_pk_bf16_f32 v65, v66, v67
	v_mov_b32_e32 v240, v64
	v_mov_b32_e32 v241, v65
	global_load_dwordx4 v[64:67], v[176:177], off offset:448
	s_nop 1
	v_permlane32_swap_b32_e32 v238, v240
	v_permlane32_swap_b32_e32 v239, v241
	global_store_dwordx4 v[250:251], v[238:241], off offset:192
	v_pk_mul_f32 v[68:69], v[118:119], v[136:137] op_sel_hi:[1,0]
	v_pk_mul_f32 v[70:71], v[124:125], v[136:137] op_sel_hi:[1,0]
	s_waitcnt vmcnt(1)
	v_pk_mul_f32 v[64:65], v[68:69], v[64:65]
	v_pk_mul_f32 v[66:67], v[70:71], v[66:67]
	v_cvt_pk_bf16_f32 v64, v64, v65
	v_cvt_pk_bf16_f32 v65, v66, v67
	v_mov_b32_e32 v242, v64
	v_mov_b32_e32 v243, v65
	global_load_dwordx4 v[64:67], v[176:177], off offset:480
	v_pk_mul_f32 v[68:69], v[122:123], v[136:137] op_sel_hi:[1,0]
	v_pk_mul_f32 v[70:71], v[126:127], v[136:137] op_sel_hi:[1,0]
	s_waitcnt vmcnt(0)
	v_pk_mul_f32 v[64:65], v[68:69], v[64:65]
	v_pk_mul_f32 v[66:67], v[70:71], v[66:67]
	v_cvt_pk_bf16_f32 v64, v64, v65
	v_cvt_pk_bf16_f32 v65, v66, v67
	v_mov_b32_e32 v244, v64
	v_mov_b32_e32 v245, v65
	s_nop 1
	v_permlane32_swap_b32_e32 v242, v244
	v_permlane32_swap_b32_e32 v243, v245
	global_store_dwordx4 v[250:251], v[242:245], off offset:224
